# dil_attn: branchless mask+bias, all K/V loads hoisted as dwordx4, PV without loads
# speedup vs baseline: 1.0221x; 1.0221x over previous
.LBB0_112:
	v_lshlrev_b32_e32 v0, s46, v194
	v_add3_u32 v191, v193, s33, v0
	v_lshrrev_b32_e32 v0, 1, v191
	v_and_b32_e32 v0, 0x7ffff0, v0
	v_or_b32_e32 v0, s41, v0
	v_add_u32_e32 v244, v193, v111
	v_lshl_or_b32 v176, v0, 9, v189
	v_subrev_u32_e32 v192, 64, v191
	v_lshl_add_u64 v[4:5], v[176:177], 1, s[38:39]
	v_add_u32_e32 v245, v192, v112
	v_add_u32_e32 v246, v191, v103
	global_load_dwordx4 v[228:231], v[4:5], off sc0 sc1
	global_load_dwordx4 v[232:235], v[4:5], off offset:1024 sc0 sc1
	global_load_dwordx4 v[236:239], v[4:5], off offset:2048 sc0 sc1
	global_load_dwordx4 v[240:243], v[4:5], off offset:3072 sc0 sc1
	s_movk_i32 s18, 0x1f0
	v_cmp_lt_i32_e32 vcc, -1, v244
	v_cmp_gt_i32_e64 s[16:17], s45, v244
	s_and_b64 vcc, vcc, s[16:17]
	v_cndmask_b32_e32 v6, v246, v245, vcc
	v_lshrrev_b32_e32 v7, 1, v6
	v_and_b32_e32 v7, 0x7ffff0, v7
	v_lshlrev_b32_e32 v6, 4, v6
	v_or_b32_e32 v7, s41, v7
	v_and_or_b32 v6, v6, s18, v113
	v_lshl_add_u32 v176, v7, 9, v6
	v_lshl_add_u64 v[4:5], v[176:177], 1, s[38:39]
	global_load_dwordx4 v[118:121], v[4:5], off sc0 sc1
	global_load_dwordx4 v[122:125], v[4:5], off offset:1024 sc0 sc1
	global_load_dwordx4 v[126:129], v[4:5], off offset:2048 sc0 sc1
	global_load_dwordx4 v[130:133], v[4:5], off offset:3072 sc0 sc1
	v_add_u32_e32 v6, 32, v244
	v_cmp_lt_i32_e32 vcc, -1, v6
	v_cmp_gt_i32_e64 s[16:17], s45, v6
	v_add_u32_e32 v7, 32, v245
	s_and_b64 vcc, vcc, s[16:17]
	v_cndmask_b32_e32 v6, v246, v7, vcc
	v_lshrrev_b32_e32 v7, 1, v6
	v_and_b32_e32 v7, 0x7ffff0, v7
	v_lshlrev_b32_e32 v6, 4, v6
	v_or_b32_e32 v7, s41, v7
	v_and_or_b32 v6, v6, s18, v113
	v_lshl_add_u32 v176, v7, 9, v6
	v_lshl_add_u64 v[4:5], v[176:177], 1, s[38:39]
	global_load_dwordx4 v[134:137], v[4:5], off sc0 sc1
	global_load_dwordx4 v[138:141], v[4:5], off offset:1024 sc0 sc1
	global_load_dwordx4 v[142:145], v[4:5], off offset:2048 sc0 sc1
	global_load_dwordx4 v[146:149], v[4:5], off offset:3072 sc0 sc1
	v_add_u32_e32 v6, 64, v244
	v_cmp_lt_i32_e32 vcc, -1, v6
	v_cmp_gt_i32_e64 s[16:17], s45, v6
	v_add_u32_e32 v7, 64, v245
	s_and_b64 vcc, vcc, s[16:17]
	v_cndmask_b32_e32 v6, v246, v7, vcc
	v_lshrrev_b32_e32 v7, 1, v6
	v_and_b32_e32 v7, 0x7ffff0, v7
	v_lshlrev_b32_e32 v6, 4, v6
	v_or_b32_e32 v7, s41, v7
	v_and_or_b32 v6, v6, s18, v113
	v_lshl_add_u32 v176, v7, 9, v6
	v_lshl_add_u64 v[4:5], v[176:177], 1, s[38:39]
	global_load_dwordx4 v[150:153], v[4:5], off sc0 sc1
	global_load_dwordx4 v[154:157], v[4:5], off offset:1024 sc0 sc1
	global_load_dwordx4 v[158:161], v[4:5], off offset:2048 sc0 sc1
	global_load_dwordx4 v[162:165], v[4:5], off offset:3072 sc0 sc1
	v_add_u32_e32 v6, 96, v244
	v_cmp_lt_i32_e32 vcc, -1, v6
	v_cmp_gt_i32_e64 s[16:17], s45, v6
	v_add_u32_e32 v7, 96, v245
	s_and_b64 vcc, vcc, s[16:17]
	v_cndmask_b32_e32 v6, v246, v7, vcc
	v_lshrrev_b32_e32 v7, 1, v6
	v_and_b32_e32 v7, 0x7ffff0, v7
	v_lshlrev_b32_e32 v6, 4, v6
	v_or_b32_e32 v7, s41, v7
	v_and_or_b32 v6, v6, s18, v113
	v_lshl_add_u32 v176, v7, 9, v6
	v_lshl_add_u64 v[4:5], v[176:177], 1, s[38:39]
	global_load_dwordx4 v[166:169], v[4:5], off sc0 sc1
	global_load_dwordx4 v[170:173], v[4:5], off offset:1024 sc0 sc1
	global_load_dwordx4 v[180:183], v[4:5], off offset:2048 sc0 sc1
	global_load_dwordx4 v[184:187], v[4:5], off offset:3072 sc0 sc1
	v_add_u32_e32 v6, 128, v244
	v_cmp_lt_i32_e32 vcc, -1, v6
	v_cmp_gt_i32_e64 s[16:17], s45, v6
	v_add_u32_e32 v7, 128, v245
	s_and_b64 vcc, vcc, s[16:17]
	v_cndmask_b32_e32 v6, v246, v7, vcc
	v_lshrrev_b32_e32 v7, 1, v6
	v_and_b32_e32 v7, 0x7ffff0, v7
	v_lshlrev_b32_e32 v6, 4, v6
	v_or_b32_e32 v7, s41, v7
	v_and_or_b32 v6, v6, s18, v113
	v_lshl_add_u32 v176, v7, 9, v6
	v_lshl_add_u64 v[4:5], v[176:177], 1, s[38:39]
	global_load_dwordx4 v[196:199], v[4:5], off sc0 sc1
	global_load_dwordx4 v[214:217], v[4:5], off offset:1024 sc0 sc1
	global_load_dwordx4 v[218:221], v[4:5], off offset:2048 sc0 sc1
	global_load_dwordx4 v[222:225], v[4:5], off offset:3072 sc0 sc1
	v_add_u32_e32 v192, v192, v100
	v_cmp_lt_i32_e32 vcc, 63, v193
	v_cmp_gt_i32_e64 s[16:17], s47, v193
	s_and_b64 s[16:17], vcc, s[16:17]
	v_cmp_lt_i32_e32 vcc, 47, v193
	v_cmp_gt_i32_e64 s[18:19], s48, v193
	s_and_b64 vcc, vcc, s[18:19]
	s_movk_i32 s20, 0xe000
	v_cndmask_b32_e64 v6, v191, v192, s[16:17]
	v_add_u32_e32 v8, 16, v192
	v_lshlrev_b32_e32 v7, 8, v6
	v_and_b32_e32 v6, 31, v6
	v_cndmask_b32_e32 v8, v191, v8, vcc
	v_and_or_b32 v6, v7, s20, v6
	v_or_b32_e32 v176, v6, v190
	v_lshl_add_u64 v[4:5], v[176:177], 1, s[2:3]
	global_load_dwordx4 v[88:91], v[4:5], off sc0 sc1
	global_load_dwordx4 v[92:95], v[4:5], off offset:2048 sc0 sc1
	v_lshlrev_b32_e32 v7, 8, v8
	v_and_b32_e32 v8, 31, v8
	v_and_or_b32 v8, v7, s20, v8
	v_or_b32_e32 v176, v8, v190
	v_lshl_add_u64 v[4:5], v[176:177], 1, s[2:3]
	global_load_dwordx4 v[80:83], v[4:5], off sc0 sc1
	global_load_dwordx4 v[84:87], v[4:5], off offset:2048 sc0 sc1
	v_readlane_b32 s18, v249, 26
	v_readlane_b32 s19, v249, 27
	s_waitcnt vmcnt(20)
	v_mfma_f32_32x32x16_bf16 v[64:79], v[118:121], v[228:231], 0
	v_mfma_f32_32x32x16_bf16 v[64:79], v[122:125], v[232:235], v[64:79]
	v_mfma_f32_32x32x16_bf16 v[64:79], v[126:129], v[236:239], v[64:79]
	v_mfma_f32_32x32x16_bf16 v[64:79], v[130:133], v[240:243], v[64:79]
	s_waitcnt vmcnt(16)
	v_mfma_f32_32x32x16_bf16 v[48:63], v[134:137], v[228:231], 0
	v_mfma_f32_32x32x16_bf16 v[48:63], v[138:141], v[232:235], v[48:63]
	v_mfma_f32_32x32x16_bf16 v[48:63], v[142:145], v[236:239], v[48:63]
	v_mfma_f32_32x32x16_bf16 v[48:63], v[146:149], v[240:243], v[48:63]
	s_waitcnt vmcnt(12)
	v_mfma_f32_32x32x16_bf16 v[32:47], v[150:153], v[228:231], 0
	v_mfma_f32_32x32x16_bf16 v[32:47], v[154:157], v[232:235], v[32:47]
	v_mfma_f32_32x32x16_bf16 v[32:47], v[158:161], v[236:239], v[32:47]
	v_mfma_f32_32x32x16_bf16 v[32:47], v[162:165], v[240:243], v[32:47]
	s_waitcnt vmcnt(8)
	v_mfma_f32_32x32x16_bf16 v[16:31], v[166:169], v[228:231], 0
	v_mfma_f32_32x32x16_bf16 v[16:31], v[170:173], v[232:235], v[16:31]
	v_mfma_f32_32x32x16_bf16 v[16:31], v[180:183], v[236:239], v[16:31]
	v_mfma_f32_32x32x16_bf16 v[16:31], v[184:187], v[240:243], v[16:31]
	s_waitcnt vmcnt(4)
	v_mfma_f32_32x32x16_bf16 v[0:15], v[196:199], v[228:231], 0
	v_mfma_f32_32x32x16_bf16 v[0:15], v[214:217], v[232:235], v[0:15]
	v_mfma_f32_32x32x16_bf16 v[0:15], v[218:221], v[236:239], v[0:15]
	v_mfma_f32_32x32x16_bf16 v[0:15], v[222:225], v[240:243], v[0:15]
	s_movk_i32 s24, 0xe000
	v_cmp_lt_i32_e64 s[20:21], 31, v193
	v_cmp_gt_i32_e64 s[22:23], s49, v193
	v_add_u32_e32 v188, 32, v192
	s_and_b64 s[20:21], s[20:21], s[22:23]
	v_cndmask_b32_e64 v188, v191, v188, s[20:21]
	v_lshlrev_b32_e32 v239, 8, v188
	v_and_b32_e32 v188, 31, v188
	v_and_or_b32 v188, v239, s24, v188
	v_or_b32_e32 v176, v188, v190
	v_lshl_add_u64 v[174:175], v[176:177], 1, s[2:3]
	global_load_dwordx4 v[118:121], v[174:175], off sc0 sc1
	global_load_dwordx4 v[122:125], v[174:175], off offset:2048 sc0 sc1
	v_cmp_lt_i32_e64 s[20:21], 15, v193
	v_cmp_gt_i32_e64 s[22:23], s50, v193
	v_add_u32_e32 v188, 48, v192
	s_and_b64 s[20:21], s[20:21], s[22:23]
	v_cndmask_b32_e64 v188, v191, v188, s[20:21]
	v_lshlrev_b32_e32 v239, 8, v188
	v_and_b32_e32 v188, 31, v188
	v_and_or_b32 v188, v239, s24, v188
	v_or_b32_e32 v176, v188, v190
	v_lshl_add_u64 v[174:175], v[176:177], 1, s[2:3]
	global_load_dwordx4 v[126:129], v[174:175], off sc0 sc1
	global_load_dwordx4 v[130:133], v[174:175], off offset:2048 sc0 sc1
	v_cmp_lt_i32_e64 s[20:21], -1, v193
	v_cmp_gt_i32_e64 s[22:23], s45, v193
	v_add_u32_e32 v188, 64, v192
	s_and_b64 s[20:21], s[20:21], s[22:23]
	v_cndmask_b32_e64 v188, v191, v188, s[20:21]
	v_lshlrev_b32_e32 v239, 8, v188
	v_and_b32_e32 v188, 31, v188
	v_and_or_b32 v188, v239, s24, v188
	v_or_b32_e32 v176, v188, v190
	v_lshl_add_u64 v[174:175], v[176:177], 1, s[2:3]
	global_load_dwordx4 v[134:137], v[174:175], off sc0 sc1
	global_load_dwordx4 v[138:141], v[174:175], off offset:2048 sc0 sc1
	s_movk_i32 s25, 0xffef
	v_cmp_lt_i32_e64 s[20:21], s25, v193
	v_cmp_gt_i32_e64 s[22:23], s51, v193
	v_add_u32_e32 v188, 80, v192
	s_and_b64 s[20:21], s[20:21], s[22:23]
	v_cndmask_b32_e64 v188, v191, v188, s[20:21]
	v_lshlrev_b32_e32 v239, 8, v188
	v_and_b32_e32 v188, 31, v188
	v_and_or_b32 v188, v239, s24, v188
	v_or_b32_e32 v176, v188, v190
	v_lshl_add_u64 v[174:175], v[176:177], 1, s[2:3]
	global_load_dwordx4 v[142:145], v[174:175], off sc0 sc1
	global_load_dwordx4 v[146:149], v[174:175], off offset:2048 sc0 sc1
	s_movk_i32 s25, 0xffdf
	v_cmp_lt_i32_e64 s[20:21], s25, v193
	v_cmp_gt_i32_e64 s[22:23], s52, v193
	v_add_u32_e32 v188, 96, v192
	s_and_b64 s[20:21], s[20:21], s[22:23]
	v_cndmask_b32_e64 v188, v191, v188, s[20:21]
	v_lshlrev_b32_e32 v239, 8, v188
	v_and_b32_e32 v188, 31, v188
	v_and_or_b32 v188, v239, s24, v188
	v_or_b32_e32 v176, v188, v190
	v_lshl_add_u64 v[174:175], v[176:177], 1, s[2:3]
	global_load_dwordx4 v[150:153], v[174:175], off sc0 sc1
	global_load_dwordx4 v[154:157], v[174:175], off offset:2048 sc0 sc1
	s_movk_i32 s25, 0xffcf
	v_cmp_lt_i32_e64 s[20:21], s25, v193
	v_cmp_gt_i32_e64 s[22:23], s53, v193
	v_add_u32_e32 v188, 112, v192
	s_and_b64 s[20:21], s[20:21], s[22:23]
	v_cndmask_b32_e64 v188, v191, v188, s[20:21]
	v_lshlrev_b32_e32 v239, 8, v188
	v_and_b32_e32 v188, 31, v188
	v_and_or_b32 v188, v239, s24, v188
	v_or_b32_e32 v176, v188, v190
	v_lshl_add_u64 v[174:175], v[176:177], 1, s[2:3]
	global_load_dwordx4 v[158:161], v[174:175], off sc0 sc1
	global_load_dwordx4 v[162:165], v[174:175], off offset:2048 sc0 sc1
	s_movk_i32 s25, 0xffbf
	v_cmp_lt_i32_e64 s[20:21], s25, v193
	v_cmp_gt_i32_e64 s[22:23], s54, v193
	v_add_u32_e32 v188, 128, v192
	s_and_b64 s[20:21], s[20:21], s[22:23]
	v_cndmask_b32_e64 v188, v191, v188, s[20:21]
	v_lshlrev_b32_e32 v239, 8, v188
	v_and_b32_e32 v188, 31, v188
	v_and_or_b32 v188, v239, s24, v188
	v_or_b32_e32 v176, v188, v190
	v_lshl_add_u64 v[174:175], v[176:177], 1, s[2:3]
	global_load_dwordx4 v[166:169], v[174:175], off sc0 sc1
	global_load_dwordx4 v[170:173], v[174:175], off offset:2048 sc0 sc1
	s_movk_i32 s25, 0xffaf
	v_cmp_lt_i32_e64 s[20:21], s25, v193
	v_cmp_gt_i32_e64 s[22:23], s55, v193
	v_add_u32_e32 v188, 144, v192
	s_and_b64 s[20:21], s[20:21], s[22:23]
	v_cndmask_b32_e64 v188, v191, v188, s[20:21]
	v_lshlrev_b32_e32 v239, 8, v188
	v_and_b32_e32 v188, 31, v188
	v_and_or_b32 v188, v239, s24, v188
	v_or_b32_e32 v176, v188, v190
	v_lshl_add_u64 v[174:175], v[176:177], 1, s[2:3]
	global_load_dwordx4 v[180:183], v[174:175], off sc0 sc1
	global_load_dwordx4 v[184:187], v[174:175], off offset:2048 sc0 sc1
	v_mov_b32_e32 v254, 0xf149f2ca
	ds_read_b32 v213, v117 offset:640
	ds_read_b32 v214, v117 offset:644
	ds_read_b32 v215, v117 offset:648
	ds_read_b32 v216, v117 offset:652
	ds_read_b32 v217, v117 offset:656
	ds_read_b32 v218, v117 offset:660
	ds_read_b32 v219, v117 offset:664
	ds_read_b32 v220, v117 offset:668
	ds_read_b32 v221, v117 offset:704
	ds_read_b32 v222, v117 offset:708
	ds_read_b32 v223, v117 offset:712
	ds_read_b32 v224, v117 offset:716
	ds_read_b32 v225, v117 offset:720
	ds_read_b32 v226, v117 offset:724
	ds_read_b32 v227, v117 offset:728
	s_and_b64 s[20:21], s[16:17], s[18:19]
	s_waitcnt lgkmcnt(10)
	v_add_f32_e32 v213, v64, v213
	v_cndmask_b32_e64 v97, v254, v213, s[20:21]
	v_readlane_b32 s18, v249, 21
	v_readlane_b32 s19, v249, 22
	s_and_b64 s[20:21], s[16:17], s[18:19]
	v_add_f32_e32 v214, v65, v214
	v_cndmask_b32_e64 v96, v254, v214, s[20:21]
	v_readlane_b32 s18, v249, 18
	v_readlane_b32 s19, v249, 19
	s_and_b64 s[20:21], s[16:17], s[18:19]
	v_add_f32_e32 v215, v66, v215
	v_cndmask_b32_e64 v65, v254, v215, s[20:21]
	v_readlane_b32 s18, v249, 30
	v_readlane_b32 s19, v249, 31
	s_and_b64 s[20:21], s[16:17], s[18:19]
	v_add_f32_e32 v216, v67, v216
	v_cndmask_b32_e64 v64, v254, v216, s[20:21]
	v_readlane_b32 s18, v249, 38
	v_readlane_b32 s19, v249, 39
	s_and_b64 s[20:21], s[16:17], s[18:19]
	v_add_f32_e32 v217, v68, v217
	v_cndmask_b32_e64 v67, v254, v217, s[20:21]
	ds_read_b32 v213, v117 offset:732
	ds_read_b32 v214, v117 offset:768
	ds_read_b32 v215, v117 offset:772
	ds_read_b32 v216, v117 offset:776
	ds_read_b32 v217, v117 offset:780
	v_readlane_b32 s18, v249, 33
	v_readlane_b32 s19, v249, 34
	s_and_b64 s[20:21], s[16:17], s[18:19]
	s_waitcnt lgkmcnt(10)
	v_add_f32_e32 v218, v69, v218
	v_cndmask_b32_e64 v66, v254, v218, s[20:21]
	s_and_b64 s[20:21], s[16:17], s[56:57]
	v_add_f32_e32 v219, v70, v219
	v_cndmask_b32_e64 v69, v254, v219, s[20:21]
	s_and_b64 s[18:19], s[16:17], s[58:59]
	v_add_f32_e32 v220, v71, v220
	v_cndmask_b32_e64 v68, v254, v220, s[18:19]
	s_and_b64 s[18:19], vcc, s[60:61]
	v_add_f32_e32 v221, v72, v221
	v_cndmask_b32_e64 v71, v254, v221, s[18:19]
	s_and_b64 s[18:19], vcc, s[62:63]
	v_add_f32_e32 v222, v73, v222
	v_cndmask_b32_e64 v70, v254, v222, s[18:19]
	ds_read_b32 v218, v117 offset:784
	ds_read_b32 v219, v117 offset:788
	ds_read_b32 v220, v117 offset:792
	ds_read_b32 v221, v117 offset:796
	ds_read_b32 v222, v117 offset:832
	s_and_b64 s[18:19], vcc, s[64:65]
	s_waitcnt lgkmcnt(10)
	v_add_f32_e32 v223, v74, v223
	v_cndmask_b32_e64 v73, v254, v223, s[18:19]
	s_and_b64 s[18:19], vcc, s[66:67]
	v_add_f32_e32 v224, v75, v224
	v_cndmask_b32_e64 v72, v254, v224, s[18:19]
	s_and_b64 s[18:19], vcc, s[68:69]
	v_add_f32_e32 v225, v76, v225
	v_cndmask_b32_e64 v75, v254, v225, s[18:19]
	s_and_b64 s[18:19], vcc, s[70:71]
	v_add_f32_e32 v226, v77, v226
	v_cndmask_b32_e64 v74, v254, v226, s[18:19]
	s_and_b64 s[18:19], vcc, s[72:73]
	v_add_f32_e32 v227, v78, v227
	v_cndmask_b32_e64 v77, v254, v227, s[18:19]
	ds_read_b32 v223, v117 offset:836
	ds_read_b32 v224, v117 offset:840
	ds_read_b32 v225, v117 offset:844
	ds_read_b32 v226, v117 offset:848
	ds_read_b32 v227, v117 offset:852
	s_and_b64 s[18:19], vcc, s[74:75]
	s_waitcnt lgkmcnt(10)
	v_add_f32_e32 v213, v79, v213
	v_cndmask_b32_e64 v76, v254, v213, s[18:19]
	v_cmp_lt_i32_e32 vcc, 31, v193
	v_cmp_gt_i32_e64 s[16:17], s49, v193
	s_and_b64 s[18:19], vcc, s[16:17]
	v_add_f32_e32 v214, v48, v214
	v_cndmask_b32_e64 v79, v254, v214, s[18:19]
	v_add_f32_e32 v215, v49, v215
	v_cndmask_b32_e64 v78, v254, v215, s[18:19]
	v_add_f32_e32 v216, v50, v216
	v_cndmask_b32_e64 v49, v254, v216, s[18:19]
	v_add_f32_e32 v217, v51, v217
	v_cndmask_b32_e64 v48, v254, v217, s[18:19]
	ds_read_b32 v213, v117 offset:856
	ds_read_b32 v214, v117 offset:860
	ds_read_b32 v215, v117 offset:896
	ds_read_b32 v216, v117 offset:900
	ds_read_b32 v217, v117 offset:904
	s_waitcnt lgkmcnt(10)
	v_add_f32_e32 v218, v52, v218
	v_cndmask_b32_e64 v51, v254, v218, s[18:19]
	v_add_f32_e32 v219, v53, v219
	v_cndmask_b32_e64 v50, v254, v219, s[18:19]
	v_add_f32_e32 v220, v54, v220
	v_cndmask_b32_e64 v53, v254, v220, s[18:19]
	v_add_f32_e32 v221, v55, v221
	v_cndmask_b32_e64 v52, v254, v221, s[18:19]
	v_cmp_lt_i32_e32 vcc, 15, v193
	v_cmp_gt_i32_e64 s[16:17], s50, v193
	s_and_b64 s[28:29], vcc, s[16:17]
	v_add_f32_e32 v222, v56, v222
	v_cndmask_b32_e64 v55, v254, v222, s[28:29]
	ds_read_b32 v218, v117 offset:908
	ds_read_b32 v219, v117 offset:912
	ds_read_b32 v220, v117 offset:916
	ds_read_b32 v221, v117 offset:920
	ds_read_b32 v222, v117 offset:924
	s_waitcnt lgkmcnt(10)
	v_add_f32_e32 v223, v57, v223
	v_cndmask_b32_e64 v54, v254, v223, s[28:29]
	v_add_f32_e32 v224, v58, v224
	v_cndmask_b32_e64 v57, v254, v224, s[28:29]
	v_add_f32_e32 v225, v59, v225
	v_cndmask_b32_e64 v56, v254, v225, s[28:29]
	v_add_f32_e32 v226, v60, v226
	v_cndmask_b32_e64 v59, v254, v226, s[28:29]
	v_add_f32_e32 v227, v61, v227
	v_cndmask_b32_e64 v58, v254, v227, s[28:29]
	ds_read_b32 v223, v117 offset:960
	ds_read_b32 v224, v117 offset:964
	ds_read_b32 v225, v117 offset:968
	ds_read_b32 v226, v117 offset:972
	ds_read_b32 v227, v117 offset:976
	s_waitcnt lgkmcnt(10)
	v_add_f32_e32 v213, v62, v213
	v_cndmask_b32_e64 v61, v254, v213, s[28:29]
	v_add_f32_e32 v214, v63, v214
	v_cndmask_b32_e64 v60, v254, v214, s[28:29]
	v_cmp_lt_i32_e32 vcc, -1, v193
	v_cmp_gt_i32_e64 s[16:17], s45, v193
	s_and_b64 s[22:23], vcc, s[16:17]
	v_add_f32_e32 v215, v32, v215
	v_cndmask_b32_e64 v63, v254, v215, s[22:23]
	v_add_f32_e32 v216, v33, v216
	v_cndmask_b32_e64 v62, v254, v216, s[22:23]
	v_add_f32_e32 v217, v34, v217
	v_cndmask_b32_e64 v98, v254, v217, s[22:23]
	ds_read_b32 v213, v117 offset:980
	ds_read_b32 v214, v117 offset:984
	ds_read_b32 v215, v117 offset:988
	ds_read_b32 v216, v117 offset:1024
	ds_read_b32 v217, v117 offset:1028
	s_waitcnt lgkmcnt(10)
	v_add_f32_e32 v218, v35, v218
	v_cndmask_b32_e64 v32, v254, v218, s[22:23]
	v_add_f32_e32 v219, v36, v219
	v_cndmask_b32_e64 v176, v254, v219, s[22:23]
	v_add_f32_e32 v220, v37, v220
	v_cndmask_b32_e64 v99, v254, v220, s[22:23]
	v_add_f32_e32 v221, v38, v221
	v_cndmask_b32_e64 v37, v254, v221, s[22:23]
	v_add_f32_e32 v222, v39, v222
	v_cndmask_b32_e64 v36, v254, v222, s[22:23]
	ds_read_b32 v218, v117 offset:1032
	ds_read_b32 v219, v117 offset:1036
	ds_read_b32 v220, v117 offset:1040
	ds_read_b32 v221, v117 offset:1044
	ds_read_b32 v222, v117 offset:1048
	s_movk_i32 s16, 0xffef
	v_cmp_lt_i32_e32 vcc, s16, v193
	v_cmp_gt_i32_e64 s[16:17], s51, v193
	s_and_b64 s[20:21], vcc, s[16:17]
	s_waitcnt lgkmcnt(10)
	v_add_f32_e32 v223, v40, v223
	v_cndmask_b32_e64 v39, v254, v223, s[20:21]
	v_add_f32_e32 v224, v41, v224
	v_cndmask_b32_e64 v38, v254, v224, s[20:21]
	v_add_f32_e32 v225, v42, v225
	v_cndmask_b32_e64 v41, v254, v225, s[20:21]
	v_add_f32_e32 v226, v43, v226
	v_cndmask_b32_e64 v40, v254, v226, s[20:21]
	v_add_f32_e32 v227, v44, v227
	v_cndmask_b32_e64 v43, v254, v227, s[20:21]
	ds_read_b32 v223, v117 offset:1052
	ds_read_b32 v224, v117 offset:1088
	ds_read_b32 v225, v117 offset:1092
	ds_read_b32 v226, v117 offset:1096
	ds_read_b32 v227, v117 offset:1100
	s_waitcnt lgkmcnt(10)
	v_add_f32_e32 v213, v45, v213
	v_cndmask_b32_e64 v42, v254, v213, s[20:21]
	v_add_f32_e32 v214, v46, v214
	v_cndmask_b32_e64 v45, v254, v214, s[20:21]
	v_add_f32_e32 v215, v47, v215
	v_cndmask_b32_e64 v44, v254, v215, s[20:21]
	s_movk_i32 s16, 0xffdf
	v_cmp_lt_i32_e32 vcc, s16, v193
	v_cmp_gt_i32_e64 s[16:17], s52, v193
	s_and_b64 s[16:17], vcc, s[16:17]
	v_add_f32_e32 v216, v16, v216
	v_cndmask_b32_e64 v47, v254, v216, s[16:17]
	v_add_f32_e32 v217, v17, v217
	v_cndmask_b32_e64 v46, v254, v217, s[16:17]
	ds_read_b32 v213, v117 offset:1104
	ds_read_b32 v214, v117 offset:1108
	ds_read_b32 v215, v117 offset:1112
	ds_read_b32 v216, v117 offset:1116
	ds_read_b32 v217, v117 offset:1152
	s_waitcnt lgkmcnt(10)
	v_add_f32_e32 v218, v18, v218
	v_cndmask_b32_e64 v17, v254, v218, s[16:17]
	v_add_f32_e32 v219, v19, v219
	v_cndmask_b32_e64 v16, v254, v219, s[16:17]
	v_add_f32_e32 v220, v20, v220
	v_cndmask_b32_e64 v19, v254, v220, s[16:17]
	v_add_f32_e32 v221, v21, v221
	v_cndmask_b32_e64 v18, v254, v221, s[16:17]
	v_add_f32_e32 v222, v22, v222
	v_cndmask_b32_e64 v21, v254, v222, s[16:17]
	ds_read_b32 v218, v117 offset:1156
	ds_read_b32 v219, v117 offset:1160
	ds_read_b32 v220, v117 offset:1164
	ds_read_b32 v221, v117 offset:1168
	ds_read_b32 v222, v117 offset:1172
	s_waitcnt lgkmcnt(10)
	v_add_f32_e32 v223, v23, v223
	v_cndmask_b32_e64 v20, v254, v223, s[16:17]
	s_movk_i32 s24, 0xffcf
	v_cmp_lt_i32_e32 vcc, s24, v193
	v_cmp_gt_i32_e64 s[24:25], s53, v193
	s_and_b64 s[24:25], vcc, s[24:25]
	v_add_f32_e32 v224, v24, v224
	v_cndmask_b32_e64 v23, v254, v224, s[24:25]
	v_add_f32_e32 v225, v25, v225
	v_cndmask_b32_e64 v22, v254, v225, s[24:25]
	v_add_f32_e32 v226, v26, v226
	v_cndmask_b32_e64 v25, v254, v226, s[24:25]
	v_add_f32_e32 v227, v27, v227
	v_cndmask_b32_e64 v24, v254, v227, s[24:25]
	ds_read_b32 v223, v117 offset:1176
	ds_read_b32 v224, v117 offset:1180
	ds_read_b32 v225, v117 offset:1216
	ds_read_b32 v226, v117 offset:1220
	ds_read_b32 v227, v117 offset:1224
	s_waitcnt lgkmcnt(10)
	v_add_f32_e32 v213, v28, v213
	v_cndmask_b32_e64 v27, v254, v213, s[24:25]
	v_add_f32_e32 v214, v29, v214
	v_cndmask_b32_e64 v26, v254, v214, s[24:25]
	v_add_f32_e32 v215, v30, v215
	v_cndmask_b32_e64 v29, v254, v215, s[24:25]
	v_add_f32_e32 v216, v31, v216
	v_cndmask_b32_e64 v28, v254, v216, s[24:25]
	s_movk_i32 s26, 0xffbf
	v_cmp_lt_i32_e32 vcc, s26, v193
	v_cmp_gt_i32_e64 s[26:27], s54, v193
	s_and_b64 s[26:27], vcc, s[26:27]
	s_and_b64 s[34:35], s[26:27], s[76:77]
	v_add_f32_e32 v217, v0, v217
	v_cndmask_b32_e64 v31, v254, v217, s[34:35]
	ds_read_b32 v213, v117 offset:1228
	ds_read_b32 v214, v117 offset:1232
	ds_read_b32 v215, v117 offset:1236
	ds_read_b32 v216, v117 offset:1240
	ds_read_b32 v217, v117 offset:1244
	s_and_b64 s[34:35], s[26:27], s[78:79]
	s_waitcnt lgkmcnt(10)
	v_add_f32_e32 v218, v1, v218
	v_cndmask_b32_e64 v30, v254, v218, s[34:35]
	s_and_b64 s[34:35], s[26:27], s[80:81]
	v_add_f32_e32 v219, v2, v219
	v_cndmask_b32_e64 v235, v254, v219, s[34:35]
	s_and_b64 s[34:35], s[26:27], s[82:83]
	v_add_f32_e32 v220, v3, v220
	v_cndmask_b32_e64 v1, v254, v220, s[34:35]
	s_and_b64 s[34:35], s[26:27], s[84:85]
	v_add_f32_e32 v221, v4, v221
	v_cndmask_b32_e64 v3, v254, v221, s[34:35]
	s_and_b64 s[34:35], s[26:27], s[86:87]
	v_add_f32_e32 v222, v5, v222
	v_cndmask_b32_e64 v2, v254, v222, s[34:35]
	s_and_b64 s[34:35], s[26:27], s[88:89]
	s_waitcnt lgkmcnt(5)
	v_add_f32_e32 v223, v6, v223
	v_cndmask_b32_e64 v5, v254, v223, s[34:35]
	s_and_b64 s[34:35], s[26:27], s[90:91]
	v_add_f32_e32 v224, v7, v224
	v_cndmask_b32_e64 v4, v254, v224, s[34:35]
	s_movk_i32 s30, 0xffaf
	v_cmp_lt_i32_e32 vcc, s30, v193
	v_cmp_gt_i32_e64 s[30:31], s55, v193
	s_and_b64 s[30:31], vcc, s[30:31]
	s_and_b64 vcc, s[30:31], s[92:93]
	v_add_f32_e32 v225, v8, v225
	v_cndmask_b32_e32 v7, v254, v225, vcc
	s_and_b64 vcc, s[30:31], s[94:95]
	v_add_f32_e32 v226, v9, v226
	v_cndmask_b32_e32 v6, v254, v226, vcc
	s_and_b64 vcc, s[30:31], s[96:97]
	v_add_f32_e32 v227, v10, v227
	v_cndmask_b32_e32 v9, v254, v227, vcc
	s_and_b64 vcc, s[30:31], s[4:5]
	s_waitcnt lgkmcnt(0)
	v_add_f32_e32 v213, v11, v213
	v_cndmask_b32_e32 v8, v254, v213, vcc
	s_and_b64 vcc, s[30:31], s[6:7]
	v_add_f32_e32 v214, v12, v214
	v_cndmask_b32_e32 v11, v254, v214, vcc
	s_and_b64 vcc, s[30:31], s[8:9]
	v_add_f32_e32 v215, v13, v215
	v_cndmask_b32_e32 v10, v254, v215, vcc
	s_and_b64 vcc, s[30:31], s[10:11]
	v_add_f32_e32 v216, v14, v216
	v_cndmask_b32_e32 v13, v254, v216, vcc
	s_and_b64 vcc, s[30:31], s[12:13]
	v_add_f32_e32 v217, v15, v217
	v_cndmask_b32_e32 v12, v254, v217, vcc
	v_add_u32_e32 v0, v193, v103
	v_lshl_add_u32 v33, v0, s44, v194
	v_cndmask_b32_e64 v15, 0, 1, s[42:43]
	v_add_u32_e32 v34, s40, v33
	v_mov_b32_e32 v0, 0
	v_mov_b32_e32 v14, 0xf149f2ca
	v_cmp_ne_u32_e64 s[34:35], 1, v15
	s_andn2_b64 vcc, exec, s[42:43]
	v_mov_b32_e32 v233, 0
	s_cbranch_vccnz .LBB0_274
	v_lshl_add_u32 v14, v34, 2, 0
	v_add_u32_e32 v15, 0x22000, v14
	v_add_u32_e32 v35, 0x22800, v14
	ds_read_b32 v14, v15
	ds_read_b32 v233, v35

.LBB0_276:
	v_cvt_pk_bf16_f32 v240, v198, v199
	v_cvt_pk_bf16_f32 v241, v201, v214
	v_cvt_pk_bf16_f32 v242, v217, v221
	v_cvt_pk_bf16_f32 v243, v222, v225
	s_waitcnt lgkmcnt(0)
	v_add_f32_e32 v68, v68, v176
	v_cvt_pk_bf16_f32 v194, v194, v195
	v_cvt_pk_bf16_f32 v195, v196, v197
	v_cvt_pk_bf16_f32 v196, v200, v213
	v_cvt_pk_bf16_f32 v197, v216, v220
	v_cvt_pk_bf16_f32 v70, v69, v70
	v_cvt_pk_bf16_f32 v71, v71, v72
	v_cvt_pk_bf16_f32 v72, v73, v74
	v_cvt_pk_bf16_f32 v73, v75, v76
	s_waitcnt vmcnt(0)
	v_mfma_f32_32x32x16_bf16 v[16:31], v[88:91], v[240:243], v[16:31]
	v_fmac_f32_e32 v68, v233, v32
	v_cvt_pk_bf16_f32 v88, v215, v218
	v_cvt_pk_bf16_f32 v89, v219, v223
	v_cvt_pk_bf16_f32 v90, v226, v229
	v_cvt_pk_bf16_f32 v91, v230, v232
	v_mfma_f32_32x32x16_bf16 v[0:15], v[92:95], v[240:243], v[0:15]
	v_cvt_pk_bf16_f32 v74, v77, v78
	v_cvt_pk_bf16_f32 v75, v79, v96
	v_cvt_pk_bf16_f32 v76, v97, v98
	v_cvt_pk_bf16_f32 v77, v99, v193
	v_cvt_pk_bf16_f32 v36, v36, v37
	v_cvt_pk_bf16_f32 v37, v38, v39
	v_cvt_pk_bf16_f32 v38, v40, v41
	v_cvt_pk_bf16_f32 v39, v42, v44
	s_andn2_b64 vcc, exec, s[36:37]
	v_mfma_f32_32x32x16_bf16 v[16:31], v[80:83], v[88:91], v[16:31]
	v_cvt_pk_bf16_f32 v80, v224, v227
	v_cvt_pk_bf16_f32 v81, v228, v231
	v_cvt_pk_bf16_f32 v82, v234, v236
	v_cvt_pk_bf16_f32 v83, v237, v238
	v_mfma_f32_32x32x16_bf16 v[0:15], v[84:87], v[88:91], v[0:15]
	v_cvt_pk_bf16_f32 v40, v43, v45
	v_cvt_pk_bf16_f32 v41, v46, v47
	v_cvt_pk_bf16_f32 v42, v48, v49
	v_cvt_pk_bf16_f32 v43, v50, v52
	v_mfma_f32_32x32x16_bf16 v[16:31], v[118:121], v[194:197], v[16:31]
	v_mfma_f32_32x32x16_bf16 v[0:15], v[122:125], v[194:197], v[0:15]
	v_cvt_pk_bf16_f32 v86, v51, v53
	v_cvt_pk_bf16_f32 v87, v54, v55
	v_cvt_pk_bf16_f32 v88, v56, v58
	v_cvt_pk_bf16_f32 v89, v59, v62
	v_mfma_f32_32x32x16_bf16 v[16:31], v[126:129], v[80:83], v[16:31]
	v_mfma_f32_32x32x16_bf16 v[0:15], v[130:133], v[80:83], v[0:15]
	v_cvt_pk_bf16_f32 v54, v57, v60
	v_cvt_pk_bf16_f32 v55, v61, v63
	v_cvt_pk_bf16_f32 v56, v64, v65
	v_cvt_pk_bf16_f32 v57, v66, v67
	s_mov_b64 s[16:17], -1
	v_mfma_f32_32x32x16_bf16 v[16:31], v[134:137], v[70:73], v[16:31]
	v_mfma_f32_32x32x16_bf16 v[0:15], v[138:141], v[70:73], v[0:15]
	v_mfma_f32_32x32x16_bf16 v[16:31], v[142:145], v[74:77], v[16:31]
	v_mfma_f32_32x32x16_bf16 v[0:15], v[146:149], v[74:77], v[0:15]
	v_mfma_f32_32x32x16_bf16 v[16:31], v[150:153], v[86:89], v[16:31]
	v_mfma_f32_32x32x16_bf16 v[0:15], v[154:157], v[86:89], v[0:15]
	v_mfma_f32_32x32x16_bf16 v[16:31], v[158:161], v[54:57], v[16:31]
	v_mfma_f32_32x32x16_bf16 v[0:15], v[162:165], v[54:57], v[0:15]
	v_mfma_f32_32x32x16_bf16 v[16:31], v[166:169], v[36:39], v[16:31]
	v_mfma_f32_32x32x16_bf16 v[0:15], v[170:173], v[36:39], v[0:15]
	v_mfma_f32_32x32x16_bf16 v[16:31], v[180:183], v[40:43], v[16:31]
	v_mfma_f32_32x32x16_bf16 v[0:15], v[184:187], v[40:43], v[0:15]
	s_cbranch_vccnz .LBB0_280
	s_mov_b64 s[16:17], exec
	v_readlane_b32 s18, v249, 63
	v_readlane_b32 s19, v248, 0
	s_and_b64 s[18:19], s[16:17], s[18:19]
	s_mov_b64 exec, s[18:19]
	s_cbranch_execz .LBB0_279
	v_lshl_add_u32 v32, v34, 2, 0
	v_add_u32_e32 v36, 0x22000, v32
	v_add_u32_e32 v32, 0x22800, v32
	ds_write_b32 v36, v35
	ds_write_b32 v32, v68

.LBB0_284:
	v_mov_b64_e32 v[180:181], 0x1598c000
	v_readlane_b32 s44, v253, 49
	v_readlane_b32 s46, v253, 47
	v_readlane_b32 s45, v253, 50
	v_readlane_b32 s40, v253, 51
	v_readlane_b32 s80, v253, 53
	v_readlane_b32 s94, v248, 1
	v_readlane_b32 s48, v249, 59
	v_readlane_b32 s6, v248, 5
	s_mov_b64 s[0:1], 0
	v_readlane_b32 s47, v253, 48
	v_readlane_b32 s41, v253, 52
	v_readlane_b32 s81, v253, 54
	v_readlane_b32 s45, v253, 57
	v_readlane_b32 s95, v248, 2
	s_movk_i32 s77, 0x100
	s_movk_i32 s94, 0x7fff
	v_readlane_b32 s49, v249, 60
	v_readlane_b32 s7, v248, 6

	.amdhsa_kernel _Z14fwd_megakernel6Params
		.amdhsa_group_segment_fixed_size 0
		.amdhsa_private_segment_fixed_size 0
		.amdhsa_kernarg_size 496
		.amdhsa_user_sgpr_count 2
		.amdhsa_user_sgpr_dispatch_ptr 0
		.amdhsa_user_sgpr_queue_ptr 0
		.amdhsa_user_sgpr_kernarg_segment_ptr 1
		.amdhsa_user_sgpr_dispatch_id 0
		.amdhsa_user_sgpr_kernarg_preload_length 0
		.amdhsa_user_sgpr_kernarg_preload_offset 0
		.amdhsa_user_sgpr_private_segment_size 0
		.amdhsa_uses_dynamic_stack 0
		.amdhsa_enable_private_segment 0
		.amdhsa_system_sgpr_workgroup_id_x 1
		.amdhsa_system_sgpr_workgroup_id_y 0
		.amdhsa_system_sgpr_workgroup_id_z 0
		.amdhsa_system_sgpr_workgroup_info 0
		.amdhsa_system_vgpr_workitem_id 2
		.amdhsa_next_free_vgpr 256
		.amdhsa_next_free_sgpr 100
		.amdhsa_accum_offset 256
		.amdhsa_reserve_vcc 1
		.amdhsa_float_round_mode_32 0
		.amdhsa_float_round_mode_16_64 0
		.amdhsa_float_denorm_mode_32 3
		.amdhsa_float_denorm_mode_16_64 3
		.amdhsa_dx10_clamp 1
		.amdhsa_ieee_mode 1
		.amdhsa_fp16_overflow 0
		.amdhsa_tg_split 0
		.amdhsa_exception_fp_ieee_invalid_op 0
		.amdhsa_exception_fp_denorm_src 0
		.amdhsa_exception_fp_ieee_div_zero 0
		.amdhsa_exception_fp_ieee_overflow 0
		.amdhsa_exception_fp_ieee_underflow 0
		.amdhsa_exception_fp_ieee_inexact 0
		.amdhsa_exception_int_div_zero 0
	.end_amdhsa_kernel

amdhsa.kernels:
  - .agpr_count:     0
    .args:
      - .offset:         0
        .size:           240
        .value_kind:     by_value
      - .offset:         240
        .size:           4
        .value_kind:     hidden_block_count_x
      - .offset:         244
        .size:           4
        .value_kind:     hidden_block_count_y
      - .offset:         248
        .size:           4
        .value_kind:     hidden_block_count_z
      - .offset:         252
        .size:           2
        .value_kind:     hidden_group_size_x
      - .offset:         254
        .size:           2
        .value_kind:     hidden_group_size_y
      - .offset:         256
        .size:           2
        .value_kind:     hidden_group_size_z
      - .offset:         258
        .size:           2
        .value_kind:     hidden_remainder_x
      - .offset:         260
        .size:           2
        .value_kind:     hidden_remainder_y
      - .offset:         262
        .size:           2
        .value_kind:     hidden_remainder_z
      - .offset:         280
        .size:           8
        .value_kind:     hidden_global_offset_x
      - .offset:         288
        .size:           8
        .value_kind:     hidden_global_offset_y
      - .offset:         296
        .size:           8
        .value_kind:     hidden_global_offset_z
      - .offset:         304
        .size:           2
        .value_kind:     hidden_grid_dims
      - .offset:         328
        .size:           8
        .value_kind:     hidden_multigrid_sync_arg
      - .offset:         360
        .size:           4
        .value_kind:     hidden_dynamic_lds_size
    .group_segment_fixed_size: 0
    .kernarg_segment_align: 8
    .kernarg_segment_size: 496
    .language:       OpenCL C
    .language_version:
      - 2
      - 0
    .max_flat_workgroup_size: 512
    .name:           _Z14fwd_megakernel6Params
    .private_segment_fixed_size: 0
    .sgpr_count:     106
    .sgpr_spill_count: 497
    .symbol:         _Z14fwd_megakernel6Params.kd
    .uniform_work_group_size: 1
    .uses_dynamic_stack: false
    .vgpr_count:     256
    .vgpr_spill_count: 0
    .wavefront_size: 64
